# adaLN inner product on f32 matrix cores (v_mfma_f32_16x16x4_f32, same f32 fma chain) and phase-0 transposes rebalanced
# speedup vs baseline: 1.0493x; 1.0054x over previous
; DI void ada_item(int it, const float* cP, const float* cS, const float* wada, const float* bada, float* mod, LAS float* red, int tid, int wave, int lane) {
;     ...
;     float acc[36];
; #pragma unroll
;     for (int b = 0; b < 36; ++b) acc[b] = 0.f;
.LBB0_705:
	s_ashr_i32 s13, s12, 31
	v_mov_b32_e32 v160, v161
	v_lshl_add_u64 v[80:81], s[12:13], 2, v[78:79]
	s_mov_b32 s8, 0
	s_mov_b64 s[6:7], -1
	v_mov_b64_e32 v[4:5], v[160:161]
	v_mov_b64_e32 v[6:7], v[160:161]
	v_mov_b64_e32 v[12:13], v[160:161]
	v_mov_b64_e32 v[14:15], v[160:161]
	v_mov_b64_e32 v[16:17], v[160:161]
	v_mov_b64_e32 v[18:19], v[160:161]
	v_mov_b64_e32 v[20:21], v[160:161]
	v_mov_b64_e32 v[22:23], v[160:161]
	v_mov_b64_e32 v[24:25], v[160:161]
	v_mov_b64_e32 v[26:27], v[160:161]
	v_mov_b64_e32 v[28:29], v[160:161]
	v_mov_b64_e32 v[30:31], v[160:161]
	s_waitcnt lgkmcnt(0)
	v_mov_b64_e32 v[32:33], v[160:161]
	v_mov_b64_e32 v[34:35], v[160:161]
	v_mov_b64_e32 v[8:9], v[160:161]
	v_mov_b64_e32 v[10:11], v[160:161]
	v_mov_b64_e32 v[0:1], v[160:161]
	v_mov_b64_e32 v[2:3], v[160:161]
	v_mov_b64_e32 v[100:101], v[160:161]
	v_mov_b64_e32 v[102:103], v[160:161]
	v_mov_b64_e32 v[104:105], v[160:161]
	v_mov_b64_e32 v[106:107], v[160:161]
	v_mov_b64_e32 v[108:109], v[160:161]
	v_mov_b64_e32 v[110:111], v[160:161]

; #define LAS __attribute__((address_space(3)))
; DI void ada_item(int it, const float* cP, const float* cS, const float* wada, const float* bada, float* mod, LAS float* red, int tid, int wave, int lane) {
;     ...
;         for (int b = 0; b < 36; ++b) { const float cv = b < 4 ? cP[b * 1024 + kb + lane] : cS[(b - 4) * 1024 + kb + lane]; cs[lane * 36 + b] = cv / (1.f + __expf(-cv)); }
;         asm volatile("s_waitcnt lgkmcnt(0)" ::: "memory");
; #pragma unroll 1
;         for (int k8 = 0; k8 < 8; ++k8) {
;             float wv[8];
; #pragma unroll
;             for (int j = 0; j < 8; ++j) wv[j] = wada[(size_t)(kb + 8 * k8 + j) * NMOD + c0 + lane];
; #pragma unroll
;             for (int j = 0; j < 8; ++j) {
;                 const LAS f32x4* cr = (const LAS f32x4*)(cs + (8 * k8 + j) * 36);
; #pragma unroll
;                 for (int q = 0; q < 9; ++q) { const f32x4 c4 = cr[q]; acc[4 * q] += c4[0] * wv[j]; acc[4 * q + 1] += c4[1] * wv[j]; acc[4 * q + 2] += c4[2] * wv[j]; acc[4 * q + 3] += c4[3] * wv[j]; }
;             }
;         }
.LBB0_707:
	s_cmpk_eq_i32 s20, 0xc00
	s_cselect_b64 vcc, -1, 0
	v_cndmask_b32_e32 v39, v37, v36, vcc
	v_add_u32_e32 v40, s20, v39
	s_and_b64 s[6:7], vcc, exec
	v_add_u32_e32 v42, 0xfffff400, v40
	v_add_u32_e32 v44, 0xfffff800, v40
	s_cselect_b32 s7, s59, s61
	s_cselect_b32 s6, s58, s60
	v_add_u32_e32 v46, 0xfffffc00, v40
	v_ashrrev_i32_e32 v43, 31, v42
	v_ashrrev_i32_e32 v45, 31, v44
	v_ashrrev_i32_e32 v41, 31, v40
	v_ashrrev_i32_e32 v47, 31, v46
	v_lshl_add_u64 v[42:43], v[42:43], 2, s[6:7]
	v_lshl_add_u64 v[44:45], v[44:45], 2, s[6:7]
	v_lshl_add_u64 v[40:41], v[40:41], 2, s[6:7]
	v_lshl_add_u64 v[46:47], v[46:47], 2, s[6:7]
	global_load_dword v39, v[42:43], off
	s_nop 0
	global_load_dword v42, v[44:45], off
	global_load_dword v43, v[46:47], off
	s_nop 0
	global_load_dword v44, v[40:41], off
	s_addk_i32 s20, 0x1000
	s_cmpk_eq_u32 s20, 0x9c00
	s_waitcnt vmcnt(3)
	v_mul_f32_e32 v40, 0xbfb8aa3b, v39
	s_waitcnt vmcnt(2)
	v_mul_f32_e32 v41, 0xbfb8aa3b, v42
	v_exp_f32_e32 v40, v40
	s_waitcnt vmcnt(1)
	v_mul_f32_e32 v45, 0xbfb8aa3b, v43
	v_exp_f32_e32 v41, v41
	s_waitcnt vmcnt(0)
	v_mul_f32_e32 v46, 0xbfb8aa3b, v44
	v_exp_f32_e32 v45, v45
	v_exp_f32_e32 v46, v46
	v_add_f32_e32 v40, 1.0, v40
	v_add_f32_e32 v41, 1.0, v41
	v_div_scale_f32 v47, s[6:7], v40, v40, v39
	v_add_f32_e32 v45, 1.0, v45
	v_div_scale_f32 v49, s[6:7], v41, v41, v42
	v_rcp_f32_e32 v55, v47
	v_add_f32_e32 v46, 1.0, v46
	v_div_scale_f32 v51, s[8:9], v45, v45, v43
	v_rcp_f32_e32 v56, v49
	v_div_scale_f32 v53, s[10:11], v46, v46, v44
	v_rcp_f32_e32 v57, v51
	v_rcp_f32_e32 v58, v53
	v_fma_f32 v59, -v47, v55, 1.0
	v_div_scale_f32 v48, vcc, v39, v40, v39
	v_fma_f32 v60, -v49, v56, 1.0
	v_fmac_f32_e32 v55, v59, v55
	v_div_scale_f32 v50, s[6:7], v42, v41, v42
	v_fma_f32 v61, -v51, v57, 1.0
	v_fmac_f32_e32 v56, v60, v56
	v_mul_f32_e32 v59, v48, v55
	v_div_scale_f32 v52, s[8:9], v43, v45, v43
	v_fma_f32 v62, -v53, v58, 1.0
	v_fmac_f32_e32 v57, v61, v57
	v_mul_f32_e32 v60, v50, v56
	v_fma_f32 v63, -v47, v59, v48
	v_div_scale_f32 v54, s[10:11], v44, v46, v44
	v_fmac_f32_e32 v58, v62, v58
	v_mul_f32_e32 v61, v52, v57
	v_fma_f32 v64, -v49, v60, v50
	v_fmac_f32_e32 v59, v63, v55
	v_mul_f32_e32 v62, v54, v58
	v_fma_f32 v65, -v51, v61, v52
	v_fmac_f32_e32 v60, v64, v56
	v_fma_f32 v47, -v47, v59, v48
	v_fma_f32 v66, -v53, v62, v54
	v_fmac_f32_e32 v61, v65, v57
	v_fma_f32 v48, -v49, v60, v50
	v_div_fmas_f32 v47, v47, v55, v59
	s_mov_b64 vcc, s[6:7]
	v_fmac_f32_e32 v62, v66, v58
	v_fma_f32 v49, -v51, v61, v52
	v_div_fixup_f32 v40, v47, v40, v39
	v_div_fmas_f32 v39, v48, v56, v60
	s_mov_b64 vcc, s[8:9]
	v_fma_f32 v50, -v53, v62, v54
	v_div_fixup_f32 v41, v39, v41, v42
	v_div_fmas_f32 v39, v49, v57, v61
	s_mov_b64 vcc, s[10:11]
	v_div_fixup_f32 v42, v39, v45, v43
	v_div_fmas_f32 v39, v50, v58, v62
	v_div_fixup_f32 v43, v39, v46, v44
	ds_write_b128 v38, v[40:43]
	v_add_u32_e32 v38, 16, v38
	s_cbranch_scc0 .LBB0_707
	s_waitcnt lgkmcnt(0)
	v_mad_i64_i32 v[82:83], s[6:7], s13, v206, v[80:81]
	s_mov_b64 s[6:7], 0
	s_mov_b32 s8, s17
	s_mul_i32 s9, s13, 0x9000
	s_lshl_b32 s10, s12, 2
	s_add_u32 s9, s9, s10
	s_add_u32 s10, s62, s9
	s_addc_u32 s11, s63, 0
	v_lshrrev_b32_e32 v94, 4, v207
	v_and_b32_e32 v96, 15, v207
	v_mul_u32_u24_e32 v95, 0x9000, v94
	v_lshl_add_u32 v95, v96, 2, v95
	v_mul_u32_u24_e32 v94, 0x90, v94
	v_lshl_add_u32 v94, v96, 2, v94
	v_add_u32_e32 v94, s17, v94
	global_load_dword v36, v95, s[10:11]
	global_load_dword v37, v95, s[10:11] offset:64
	global_load_dword v38, v95, s[10:11] offset:128
	global_load_dword v39, v95, s[10:11] offset:192
	v_add_u32_e32 v95, 0x24000, v95
	global_load_dword v40, v95, s[10:11]
	global_load_dword v41, v95, s[10:11] offset:64
	global_load_dword v42, v95, s[10:11] offset:128
	global_load_dword v43, v95, s[10:11] offset:192
	v_add_u32_e32 v95, 0x24000, v95
	global_load_dword v44, v95, s[10:11]
	global_load_dword v45, v95, s[10:11] offset:64
	global_load_dword v46, v95, s[10:11] offset:128
	global_load_dword v47, v95, s[10:11] offset:192
	v_add_u32_e32 v95, 0x24000, v95
	global_load_dword v48, v95, s[10:11]
	global_load_dword v49, v95, s[10:11] offset:64
	global_load_dword v50, v95, s[10:11] offset:128
	global_load_dword v51, v95, s[10:11] offset:192
	v_add_u32_e32 v95, 0x24000, v95
	global_load_dword v52, v95, s[10:11]
	global_load_dword v53, v95, s[10:11] offset:64
	global_load_dword v54, v95, s[10:11] offset:128
	global_load_dword v55, v95, s[10:11] offset:192
	v_add_u32_e32 v95, 0x24000, v95
	global_load_dword v56, v95, s[10:11]
	global_load_dword v57, v95, s[10:11] offset:64
	global_load_dword v58, v95, s[10:11] offset:128
	global_load_dword v59, v95, s[10:11] offset:192
	v_add_u32_e32 v95, 0x24000, v95
	global_load_dword v60, v95, s[10:11]
	global_load_dword v61, v95, s[10:11] offset:64
	global_load_dword v62, v95, s[10:11] offset:128
	global_load_dword v63, v95, s[10:11] offset:192
	v_add_u32_e32 v95, 0x24000, v95
	global_load_dword v64, v95, s[10:11]
	global_load_dword v65, v95, s[10:11] offset:64
	global_load_dword v66, v95, s[10:11] offset:128
	global_load_dword v67, v95, s[10:11] offset:192
	v_add_u32_e32 v95, 0x24000, v95
	ds_read_b32 v112, v94
	ds_read_b32 v113, v94 offset:64
	ds_read_b32 v114, v94 offset:128
	ds_read_b32 v115, v94 offset:576
	ds_read_b32 v116, v94 offset:640
	ds_read_b32 v117, v94 offset:704
	ds_read_b32 v118, v94 offset:1152
	ds_read_b32 v119, v94 offset:1216
	ds_read_b32 v120, v94 offset:1280
	ds_read_b32 v121, v94 offset:1728
	ds_read_b32 v122, v94 offset:1792
	ds_read_b32 v123, v94 offset:1856
	ds_read_b32 v124, v94 offset:2304
	ds_read_b32 v125, v94 offset:2368
	ds_read_b32 v126, v94 offset:2432
	ds_read_b32 v127, v94 offset:2880
	ds_read_b32 v128, v94 offset:2944
	ds_read_b32 v129, v94 offset:3008
	ds_read_b32 v130, v94 offset:3456
	ds_read_b32 v131, v94 offset:3520
	ds_read_b32 v132, v94 offset:3584
	ds_read_b32 v133, v94 offset:4032
	ds_read_b32 v134, v94 offset:4096
	ds_read_b32 v135, v94 offset:4160
	ds_read_b32 v136, v94 offset:4608
	ds_read_b32 v137, v94 offset:4672
	ds_read_b32 v138, v94 offset:4736
	ds_read_b32 v139, v94 offset:5184
	ds_read_b32 v140, v94 offset:5248
	ds_read_b32 v141, v94 offset:5312
	ds_read_b32 v142, v94 offset:5760
	ds_read_b32 v143, v94 offset:5824
	ds_read_b32 v144, v94 offset:5888
	ds_read_b32 v145, v94 offset:6336
	ds_read_b32 v146, v94 offset:6400
	ds_read_b32 v147, v94 offset:6464
	ds_read_b32 v148, v94 offset:6912
	ds_read_b32 v149, v94 offset:6976
	ds_read_b32 v150, v94 offset:7040
	ds_read_b32 v151, v94 offset:7488
	ds_read_b32 v152, v94 offset:7552
	ds_read_b32 v153, v94 offset:7616
	ds_read_b32 v154, v94 offset:8064
	ds_read_b32 v155, v94 offset:8128
	ds_read_b32 v156, v94 offset:8192
	ds_read_b32 v157, v94 offset:8640
	ds_read_b32 v158, v94 offset:8704
	ds_read_b32 v159, v94 offset:8768
	s_waitcnt vmcnt(28) lgkmcnt(15)
; #define LAS __attribute__((address_space(3)))
; DI void ada_item(int it, const float* cP, const float* cS, const float* wada, const float* bada, float* mod, LAS float* red, int tid, int wave, int lane) {
;     ...
;         for (int k8 = 0; k8 < 8; ++k8) {
;             float wv[8];
; #pragma unroll
;             for (int j = 0; j < 8; ++j) wv[j] = wada[(size_t)(kb + 8 * k8 + j) * NMOD + c0 + lane];
; #pragma unroll
;             for (int j = 0; j < 8; ++j) {
;                 const LAS f32x4* cr = (const LAS f32x4*)(cs + (8 * k8 + j) * 36);
; #pragma unroll
;                 for (int q = 0; q < 9; ++q) { const f32x4 c4 = cr[q]; acc[4 * q] += c4[0] * wv[j]; acc[4 * q + 1] += c4[1] * wv[j]; acc[4 * q + 2] += c4[2] * wv[j]; acc[4 * q + 3] += c4[3] * wv[j]; }
;             }
	v_mfma_f32_16x16x4_f32 v[0:3], v112, v36, v[0:3]
	v_mfma_f32_16x16x4_f32 v[4:7], v112, v37, v[4:7]
	v_mfma_f32_16x16x4_f32 v[8:11], v112, v38, v[8:11]
	v_mfma_f32_16x16x4_f32 v[12:15], v112, v39, v[12:15]
	v_mfma_f32_16x16x4_f32 v[16:19], v113, v36, v[16:19]
	v_mfma_f32_16x16x4_f32 v[20:23], v113, v37, v[20:23]
	v_mfma_f32_16x16x4_f32 v[24:27], v113, v38, v[24:27]
	v_mfma_f32_16x16x4_f32 v[28:31], v113, v39, v[28:31]
	v_mfma_f32_16x16x4_f32 v[32:35], v114, v36, v[32:35]
	v_mfma_f32_16x16x4_f32 v[100:103], v114, v37, v[100:103]
	v_mfma_f32_16x16x4_f32 v[104:107], v114, v38, v[104:107]
	v_mfma_f32_16x16x4_f32 v[108:111], v114, v39, v[108:111]
	global_load_dword v36, v95, s[10:11]
	global_load_dword v37, v95, s[10:11] offset:64
	global_load_dword v38, v95, s[10:11] offset:128
	global_load_dword v39, v95, s[10:11] offset:192
	v_add_u32_e32 v95, 0x24000, v95
	s_waitcnt vmcnt(28) lgkmcnt(15)
	v_mfma_f32_16x16x4_f32 v[0:3], v115, v40, v[0:3]
	v_mfma_f32_16x16x4_f32 v[4:7], v115, v41, v[4:7]
	v_mfma_f32_16x16x4_f32 v[8:11], v115, v42, v[8:11]
	v_mfma_f32_16x16x4_f32 v[12:15], v115, v43, v[12:15]
	v_mfma_f32_16x16x4_f32 v[16:19], v116, v40, v[16:19]
	v_mfma_f32_16x16x4_f32 v[20:23], v116, v41, v[20:23]
	v_mfma_f32_16x16x4_f32 v[24:27], v116, v42, v[24:27]
	v_mfma_f32_16x16x4_f32 v[28:31], v116, v43, v[28:31]
	v_mfma_f32_16x16x4_f32 v[32:35], v117, v40, v[32:35]
	v_mfma_f32_16x16x4_f32 v[100:103], v117, v41, v[100:103]
	v_mfma_f32_16x16x4_f32 v[104:107], v117, v42, v[104:107]
	v_mfma_f32_16x16x4_f32 v[108:111], v117, v43, v[108:111]
	global_load_dword v40, v95, s[10:11]
	global_load_dword v41, v95, s[10:11] offset:64
	global_load_dword v42, v95, s[10:11] offset:128
	global_load_dword v43, v95, s[10:11] offset:192
	v_add_u32_e32 v95, 0x24000, v95
	s_waitcnt vmcnt(28) lgkmcnt(15)
	v_mfma_f32_16x16x4_f32 v[0:3], v118, v44, v[0:3]
	v_mfma_f32_16x16x4_f32 v[4:7], v118, v45, v[4:7]
	v_mfma_f32_16x16x4_f32 v[8:11], v118, v46, v[8:11]
	v_mfma_f32_16x16x4_f32 v[12:15], v118, v47, v[12:15]
	v_mfma_f32_16x16x4_f32 v[16:19], v119, v44, v[16:19]
	v_mfma_f32_16x16x4_f32 v[20:23], v119, v45, v[20:23]
	v_mfma_f32_16x16x4_f32 v[24:27], v119, v46, v[24:27]
	v_mfma_f32_16x16x4_f32 v[28:31], v119, v47, v[28:31]
	v_mfma_f32_16x16x4_f32 v[32:35], v120, v44, v[32:35]
	v_mfma_f32_16x16x4_f32 v[100:103], v120, v45, v[100:103]
	v_mfma_f32_16x16x4_f32 v[104:107], v120, v46, v[104:107]
	v_mfma_f32_16x16x4_f32 v[108:111], v120, v47, v[108:111]
	global_load_dword v44, v95, s[10:11]
	global_load_dword v45, v95, s[10:11] offset:64
	global_load_dword v46, v95, s[10:11] offset:128
	global_load_dword v47, v95, s[10:11] offset:192
	v_add_u32_e32 v95, 0x24000, v95
	s_waitcnt vmcnt(28) lgkmcnt(15)
	v_mfma_f32_16x16x4_f32 v[0:3], v121, v48, v[0:3]
	v_mfma_f32_16x16x4_f32 v[4:7], v121, v49, v[4:7]
	v_mfma_f32_16x16x4_f32 v[8:11], v121, v50, v[8:11]
	v_mfma_f32_16x16x4_f32 v[12:15], v121, v51, v[12:15]
	v_mfma_f32_16x16x4_f32 v[16:19], v122, v48, v[16:19]
	v_mfma_f32_16x16x4_f32 v[20:23], v122, v49, v[20:23]
	v_mfma_f32_16x16x4_f32 v[24:27], v122, v50, v[24:27]
	v_mfma_f32_16x16x4_f32 v[28:31], v122, v51, v[28:31]
	v_mfma_f32_16x16x4_f32 v[32:35], v123, v48, v[32:35]
	v_mfma_f32_16x16x4_f32 v[100:103], v123, v49, v[100:103]
	v_mfma_f32_16x16x4_f32 v[104:107], v123, v50, v[104:107]
	v_mfma_f32_16x16x4_f32 v[108:111], v123, v51, v[108:111]
	global_load_dword v48, v95, s[10:11]
	global_load_dword v49, v95, s[10:11] offset:64
	global_load_dword v50, v95, s[10:11] offset:128
	global_load_dword v51, v95, s[10:11] offset:192
	v_add_u32_e32 v95, 0x24000, v95
	s_waitcnt vmcnt(28) lgkmcnt(15)
	v_mfma_f32_16x16x4_f32 v[0:3], v124, v52, v[0:3]
	v_mfma_f32_16x16x4_f32 v[4:7], v124, v53, v[4:7]
	v_mfma_f32_16x16x4_f32 v[8:11], v124, v54, v[8:11]
	v_mfma_f32_16x16x4_f32 v[12:15], v124, v55, v[12:15]
	v_mfma_f32_16x16x4_f32 v[16:19], v125, v52, v[16:19]
	v_mfma_f32_16x16x4_f32 v[20:23], v125, v53, v[20:23]
	v_mfma_f32_16x16x4_f32 v[24:27], v125, v54, v[24:27]
	v_mfma_f32_16x16x4_f32 v[28:31], v125, v55, v[28:31]
	v_mfma_f32_16x16x4_f32 v[32:35], v126, v52, v[32:35]
	v_mfma_f32_16x16x4_f32 v[100:103], v126, v53, v[100:103]
	v_mfma_f32_16x16x4_f32 v[104:107], v126, v54, v[104:107]
	v_mfma_f32_16x16x4_f32 v[108:111], v126, v55, v[108:111]
	global_load_dword v52, v95, s[10:11]
	global_load_dword v53, v95, s[10:11] offset:64
	global_load_dword v54, v95, s[10:11] offset:128
	global_load_dword v55, v95, s[10:11] offset:192
	v_add_u32_e32 v95, 0x24000, v95
	s_waitcnt vmcnt(28) lgkmcnt(15)
	v_mfma_f32_16x16x4_f32 v[0:3], v127, v56, v[0:3]
	v_mfma_f32_16x16x4_f32 v[4:7], v127, v57, v[4:7]
	v_mfma_f32_16x16x4_f32 v[8:11], v127, v58, v[8:11]
	v_mfma_f32_16x16x4_f32 v[12:15], v127, v59, v[12:15]
	v_mfma_f32_16x16x4_f32 v[16:19], v128, v56, v[16:19]
	v_mfma_f32_16x16x4_f32 v[20:23], v128, v57, v[20:23]
	v_mfma_f32_16x16x4_f32 v[24:27], v128, v58, v[24:27]
	v_mfma_f32_16x16x4_f32 v[28:31], v128, v59, v[28:31]
	v_mfma_f32_16x16x4_f32 v[32:35], v129, v56, v[32:35]
	v_mfma_f32_16x16x4_f32 v[100:103], v129, v57, v[100:103]
	v_mfma_f32_16x16x4_f32 v[104:107], v129, v58, v[104:107]
	v_mfma_f32_16x16x4_f32 v[108:111], v129, v59, v[108:111]
	global_load_dword v56, v95, s[10:11]
	global_load_dword v57, v95, s[10:11] offset:64
	global_load_dword v58, v95, s[10:11] offset:128
	global_load_dword v59, v95, s[10:11] offset:192
	v_add_u32_e32 v95, 0x24000, v95
	s_waitcnt vmcnt(28) lgkmcnt(15)
; #define LAS __attribute__((address_space(3)))
; DI void ada_item(int it, const float* cP, const float* cS, const float* wada, const float* bada, float* mod, LAS float* red, int tid, int wave, int lane) {
;     ...
;         for (int k8 = 0; k8 < 8; ++k8) {
;             float wv[8];
; #pragma unroll
;             for (int j = 0; j < 8; ++j) wv[j] = wada[(size_t)(kb + 8 * k8 + j) * NMOD + c0 + lane];
; #pragma unroll
;             for (int j = 0; j < 8; ++j) {
;                 const LAS f32x4* cr = (const LAS f32x4*)(cs + (8 * k8 + j) * 36);
; #pragma unroll
;                 for (int q = 0; q < 9; ++q) { const f32x4 c4 = cr[q]; acc[4 * q] += c4[0] * wv[j]; acc[4 * q + 1] += c4[1] * wv[j]; acc[4 * q + 2] += c4[2] * wv[j]; acc[4 * q + 3] += c4[3] * wv[j]; }
;             }
	v_mfma_f32_16x16x4_f32 v[0:3], v130, v60, v[0:3]
	v_mfma_f32_16x16x4_f32 v[4:7], v130, v61, v[4:7]
	v_mfma_f32_16x16x4_f32 v[8:11], v130, v62, v[8:11]
	v_mfma_f32_16x16x4_f32 v[12:15], v130, v63, v[12:15]
	v_mfma_f32_16x16x4_f32 v[16:19], v131, v60, v[16:19]
	v_mfma_f32_16x16x4_f32 v[20:23], v131, v61, v[20:23]
	v_mfma_f32_16x16x4_f32 v[24:27], v131, v62, v[24:27]
	v_mfma_f32_16x16x4_f32 v[28:31], v131, v63, v[28:31]
	v_mfma_f32_16x16x4_f32 v[32:35], v132, v60, v[32:35]
	v_mfma_f32_16x16x4_f32 v[100:103], v132, v61, v[100:103]
	v_mfma_f32_16x16x4_f32 v[104:107], v132, v62, v[104:107]
	v_mfma_f32_16x16x4_f32 v[108:111], v132, v63, v[108:111]
	global_load_dword v60, v95, s[10:11]
	global_load_dword v61, v95, s[10:11] offset:64
	global_load_dword v62, v95, s[10:11] offset:128
	global_load_dword v63, v95, s[10:11] offset:192
	v_add_u32_e32 v95, 0x24000, v95
	s_waitcnt vmcnt(28) lgkmcnt(15)
	v_mfma_f32_16x16x4_f32 v[0:3], v133, v64, v[0:3]
	v_mfma_f32_16x16x4_f32 v[4:7], v133, v65, v[4:7]
	v_mfma_f32_16x16x4_f32 v[8:11], v133, v66, v[8:11]
	v_mfma_f32_16x16x4_f32 v[12:15], v133, v67, v[12:15]
	v_mfma_f32_16x16x4_f32 v[16:19], v134, v64, v[16:19]
	v_mfma_f32_16x16x4_f32 v[20:23], v134, v65, v[20:23]
	v_mfma_f32_16x16x4_f32 v[24:27], v134, v66, v[24:27]
	v_mfma_f32_16x16x4_f32 v[28:31], v134, v67, v[28:31]
	v_mfma_f32_16x16x4_f32 v[32:35], v135, v64, v[32:35]
	v_mfma_f32_16x16x4_f32 v[100:103], v135, v65, v[100:103]
	v_mfma_f32_16x16x4_f32 v[104:107], v135, v66, v[104:107]
	v_mfma_f32_16x16x4_f32 v[108:111], v135, v67, v[108:111]
	global_load_dword v64, v95, s[10:11]
	global_load_dword v65, v95, s[10:11] offset:64
	global_load_dword v66, v95, s[10:11] offset:128
	global_load_dword v67, v95, s[10:11] offset:192
	v_add_u32_e32 v95, 0x24000, v95
	s_waitcnt vmcnt(28) lgkmcnt(15)
	v_mfma_f32_16x16x4_f32 v[0:3], v136, v36, v[0:3]
	v_mfma_f32_16x16x4_f32 v[4:7], v136, v37, v[4:7]
	v_mfma_f32_16x16x4_f32 v[8:11], v136, v38, v[8:11]
	v_mfma_f32_16x16x4_f32 v[12:15], v136, v39, v[12:15]
	v_mfma_f32_16x16x4_f32 v[16:19], v137, v36, v[16:19]
	v_mfma_f32_16x16x4_f32 v[20:23], v137, v37, v[20:23]
	v_mfma_f32_16x16x4_f32 v[24:27], v137, v38, v[24:27]
	v_mfma_f32_16x16x4_f32 v[28:31], v137, v39, v[28:31]
	v_mfma_f32_16x16x4_f32 v[32:35], v138, v36, v[32:35]
	v_mfma_f32_16x16x4_f32 v[100:103], v138, v37, v[100:103]
	v_mfma_f32_16x16x4_f32 v[104:107], v138, v38, v[104:107]
	v_mfma_f32_16x16x4_f32 v[108:111], v138, v39, v[108:111]
	s_waitcnt vmcnt(24) lgkmcnt(15)
	v_mfma_f32_16x16x4_f32 v[0:3], v139, v40, v[0:3]
	v_mfma_f32_16x16x4_f32 v[4:7], v139, v41, v[4:7]
	v_mfma_f32_16x16x4_f32 v[8:11], v139, v42, v[8:11]
	v_mfma_f32_16x16x4_f32 v[12:15], v139, v43, v[12:15]
	v_mfma_f32_16x16x4_f32 v[16:19], v140, v40, v[16:19]
	v_mfma_f32_16x16x4_f32 v[20:23], v140, v41, v[20:23]
	v_mfma_f32_16x16x4_f32 v[24:27], v140, v42, v[24:27]
	v_mfma_f32_16x16x4_f32 v[28:31], v140, v43, v[28:31]
	v_mfma_f32_16x16x4_f32 v[32:35], v141, v40, v[32:35]
	v_mfma_f32_16x16x4_f32 v[100:103], v141, v41, v[100:103]
	v_mfma_f32_16x16x4_f32 v[104:107], v141, v42, v[104:107]
	v_mfma_f32_16x16x4_f32 v[108:111], v141, v43, v[108:111]
	s_waitcnt vmcnt(20) lgkmcnt(15)
	v_mfma_f32_16x16x4_f32 v[0:3], v142, v44, v[0:3]
	v_mfma_f32_16x16x4_f32 v[4:7], v142, v45, v[4:7]
	v_mfma_f32_16x16x4_f32 v[8:11], v142, v46, v[8:11]
	v_mfma_f32_16x16x4_f32 v[12:15], v142, v47, v[12:15]
	v_mfma_f32_16x16x4_f32 v[16:19], v143, v44, v[16:19]
	v_mfma_f32_16x16x4_f32 v[20:23], v143, v45, v[20:23]
	v_mfma_f32_16x16x4_f32 v[24:27], v143, v46, v[24:27]
	v_mfma_f32_16x16x4_f32 v[28:31], v143, v47, v[28:31]
	v_mfma_f32_16x16x4_f32 v[32:35], v144, v44, v[32:35]
	v_mfma_f32_16x16x4_f32 v[100:103], v144, v45, v[100:103]
	v_mfma_f32_16x16x4_f32 v[104:107], v144, v46, v[104:107]
	v_mfma_f32_16x16x4_f32 v[108:111], v144, v47, v[108:111]
	s_waitcnt vmcnt(16) lgkmcnt(12)
	v_mfma_f32_16x16x4_f32 v[0:3], v145, v48, v[0:3]
	v_mfma_f32_16x16x4_f32 v[4:7], v145, v49, v[4:7]
	v_mfma_f32_16x16x4_f32 v[8:11], v145, v50, v[8:11]
	v_mfma_f32_16x16x4_f32 v[12:15], v145, v51, v[12:15]
	v_mfma_f32_16x16x4_f32 v[16:19], v146, v48, v[16:19]
	v_mfma_f32_16x16x4_f32 v[20:23], v146, v49, v[20:23]
	v_mfma_f32_16x16x4_f32 v[24:27], v146, v50, v[24:27]
	v_mfma_f32_16x16x4_f32 v[28:31], v146, v51, v[28:31]
	v_mfma_f32_16x16x4_f32 v[32:35], v147, v48, v[32:35]
	v_mfma_f32_16x16x4_f32 v[100:103], v147, v49, v[100:103]
	v_mfma_f32_16x16x4_f32 v[104:107], v147, v50, v[104:107]
	v_mfma_f32_16x16x4_f32 v[108:111], v147, v51, v[108:111]
	s_waitcnt vmcnt(12) lgkmcnt(9)
	v_mfma_f32_16x16x4_f32 v[0:3], v148, v52, v[0:3]
	v_mfma_f32_16x16x4_f32 v[4:7], v148, v53, v[4:7]
	v_mfma_f32_16x16x4_f32 v[8:11], v148, v54, v[8:11]
	v_mfma_f32_16x16x4_f32 v[12:15], v148, v55, v[12:15]
	v_mfma_f32_16x16x4_f32 v[16:19], v149, v52, v[16:19]
	v_mfma_f32_16x16x4_f32 v[20:23], v149, v53, v[20:23]
	v_mfma_f32_16x16x4_f32 v[24:27], v149, v54, v[24:27]
	v_mfma_f32_16x16x4_f32 v[28:31], v149, v55, v[28:31]
	v_mfma_f32_16x16x4_f32 v[32:35], v150, v52, v[32:35]
	v_mfma_f32_16x16x4_f32 v[100:103], v150, v53, v[100:103]
	v_mfma_f32_16x16x4_f32 v[104:107], v150, v54, v[104:107]
	v_mfma_f32_16x16x4_f32 v[108:111], v150, v55, v[108:111]
	s_waitcnt vmcnt(8) lgkmcnt(6)
; #define LAS __attribute__((address_space(3)))
; DI void ada_item(int it, const float* cP, const float* cS, const float* wada, const float* bada, float* mod, LAS float* red, int tid, int wave, int lane) {
;     ...
; #pragma unroll
;             for (int j = 0; j < 8; ++j) {
;                 const LAS f32x4* cr = (const LAS f32x4*)(cs + (8 * k8 + j) * 36);
; #pragma unroll
;                 for (int q = 0; q < 9; ++q) { const f32x4 c4 = cr[q]; acc[4 * q] += c4[0] * wv[j]; acc[4 * q + 1] += c4[1] * wv[j]; acc[4 * q + 2] += c4[2] * wv[j]; acc[4 * q + 3] += c4[3] * wv[j]; }
;             }
;         }
;         asm volatile("s_waitcnt lgkmcnt(0)" ::: "memory");
;     }
;     __syncthreads();
; #pragma unroll
;     for (int b = 0; b < 36; ++b) red[(wave * 36 + b) * 64 + lane] = acc[b];
;     __syncthreads();
	v_mfma_f32_16x16x4_f32 v[0:3], v151, v56, v[0:3]
	v_mfma_f32_16x16x4_f32 v[4:7], v151, v57, v[4:7]
	v_mfma_f32_16x16x4_f32 v[8:11], v151, v58, v[8:11]
	v_mfma_f32_16x16x4_f32 v[12:15], v151, v59, v[12:15]
	v_mfma_f32_16x16x4_f32 v[16:19], v152, v56, v[16:19]
	v_mfma_f32_16x16x4_f32 v[20:23], v152, v57, v[20:23]
	v_mfma_f32_16x16x4_f32 v[24:27], v152, v58, v[24:27]
	v_mfma_f32_16x16x4_f32 v[28:31], v152, v59, v[28:31]
	v_mfma_f32_16x16x4_f32 v[32:35], v153, v56, v[32:35]
	v_mfma_f32_16x16x4_f32 v[100:103], v153, v57, v[100:103]
	v_mfma_f32_16x16x4_f32 v[104:107], v153, v58, v[104:107]
	v_mfma_f32_16x16x4_f32 v[108:111], v153, v59, v[108:111]
	s_waitcnt vmcnt(4) lgkmcnt(3)
	v_mfma_f32_16x16x4_f32 v[0:3], v154, v60, v[0:3]
	v_mfma_f32_16x16x4_f32 v[4:7], v154, v61, v[4:7]
	v_mfma_f32_16x16x4_f32 v[8:11], v154, v62, v[8:11]
	v_mfma_f32_16x16x4_f32 v[12:15], v154, v63, v[12:15]
	v_mfma_f32_16x16x4_f32 v[16:19], v155, v60, v[16:19]
	v_mfma_f32_16x16x4_f32 v[20:23], v155, v61, v[20:23]
	v_mfma_f32_16x16x4_f32 v[24:27], v155, v62, v[24:27]
	v_mfma_f32_16x16x4_f32 v[28:31], v155, v63, v[28:31]
	v_mfma_f32_16x16x4_f32 v[32:35], v156, v60, v[32:35]
	v_mfma_f32_16x16x4_f32 v[100:103], v156, v61, v[100:103]
	v_mfma_f32_16x16x4_f32 v[104:107], v156, v62, v[104:107]
	v_mfma_f32_16x16x4_f32 v[108:111], v156, v63, v[108:111]
	s_waitcnt vmcnt(0) lgkmcnt(0)
	v_mfma_f32_16x16x4_f32 v[0:3], v157, v64, v[0:3]
	v_mfma_f32_16x16x4_f32 v[4:7], v157, v65, v[4:7]
	v_mfma_f32_16x16x4_f32 v[8:11], v157, v66, v[8:11]
	v_mfma_f32_16x16x4_f32 v[12:15], v157, v67, v[12:15]
	v_mfma_f32_16x16x4_f32 v[16:19], v158, v64, v[16:19]
	v_mfma_f32_16x16x4_f32 v[20:23], v158, v65, v[20:23]
	v_mfma_f32_16x16x4_f32 v[24:27], v158, v66, v[24:27]
	v_mfma_f32_16x16x4_f32 v[28:31], v158, v67, v[28:31]
	v_mfma_f32_16x16x4_f32 v[32:35], v159, v64, v[32:35]
	v_mfma_f32_16x16x4_f32 v[100:103], v159, v65, v[100:103]
	v_mfma_f32_16x16x4_f32 v[104:107], v159, v66, v[104:107]
	v_mfma_f32_16x16x4_f32 v[108:111], v159, v67, v[108:111]
	s_waitcnt lgkmcnt(0)
	s_mov_b32 s8, 64
	s_mov_b64 s[6:7], 0
	s_and_b64 vcc, exec, s[14:15]
	s_cbranch_vccz .LBB0_706
	v_lshrrev_b32_e32 v36, 4, v207
	v_and_b32_e32 v37, 15, v207
	v_lshlrev_b32_e32 v36, 10, v36
	v_lshl_add_u32 v36, v37, 2, v36
	v_add_u32_e32 v36, s16, v36
	s_nop 15
	s_barrier
	ds_write_b32 v36, v0
	ds_write_b32 v36, v1 offset:256
	ds_write_b32 v36, v2 offset:512
	ds_write_b32 v36, v3 offset:768
	ds_write_b32 v36, v4 offset:64
	ds_write_b32 v36, v5 offset:320
	ds_write_b32 v36, v6 offset:576
	ds_write_b32 v36, v7 offset:832
	ds_write_b32 v36, v8 offset:128
	ds_write_b32 v36, v9 offset:384
	ds_write_b32 v36, v10 offset:640
	ds_write_b32 v36, v11 offset:896
	ds_write_b32 v36, v12 offset:192
	ds_write_b32 v36, v13 offset:448
	ds_write_b32 v36, v14 offset:704
	ds_write_b32 v36, v15 offset:960
	ds_write_b32 v36, v16 offset:4096
	ds_write_b32 v36, v17 offset:4352
	ds_write_b32 v36, v18 offset:4608
	ds_write_b32 v36, v19 offset:4864
	ds_write_b32 v36, v20 offset:4160
	ds_write_b32 v36, v21 offset:4416
	ds_write_b32 v36, v22 offset:4672
	ds_write_b32 v36, v23 offset:4928
	ds_write_b32 v36, v24 offset:4224
	ds_write_b32 v36, v25 offset:4480
	ds_write_b32 v36, v26 offset:4736
	ds_write_b32 v36, v27 offset:4992
	ds_write_b32 v36, v28 offset:4288
	ds_write_b32 v36, v29 offset:4544
	ds_write_b32 v36, v30 offset:4800
	ds_write_b32 v36, v31 offset:5056
	s_mov_b64 exec, 0xffff
	ds_write_b32 v36, v32 offset:8192
	ds_write_b32 v36, v33 offset:8448
	ds_write_b32 v36, v34 offset:8704
	ds_write_b32 v36, v35 offset:8960
	ds_write_b32 v36, v100 offset:8256
	ds_write_b32 v36, v101 offset:8512
	ds_write_b32 v36, v102 offset:8768
	ds_write_b32 v36, v103 offset:9024
	ds_write_b32 v36, v104 offset:8320
	ds_write_b32 v36, v105 offset:8576
	ds_write_b32 v36, v106 offset:8832
	ds_write_b32 v36, v107 offset:9088
	ds_write_b32 v36, v108 offset:8384
	ds_write_b32 v36, v109 offset:8640
	ds_write_b32 v36, v110 offset:8896
	ds_write_b32 v36, v111 offset:9152
	s_mov_b64 exec, -1
	s_waitcnt lgkmcnt(0)
	s_barrier
	s_and_saveexec_b64 s[6:7], s[4:5]
	s_cbranch_execz .LBB0_704
	s_lshl_b32 s8, s19, 6
	v_readlane_b32 s84, v253, 0
	v_or_b32_e32 v0, s8, v207
	v_readlane_b32 s88, v253, 4
	v_readlane_b32 s89, v253, 5
	v_readlane_b32 s90, v253, 6
	v_readlane_b32 s91, v253, 7
	v_readlane_b32 s94, v253, 10
	v_readlane_b32 s95, v253, 11
	v_readlane_b32 s98, v253, 14
	v_readlane_b32 s99, v253, 15
	s_ashr_i32 s9, s8, 31
	v_ashrrev_i32_e32 v1, 31, v0
	v_readlane_b32 s85, v253, 1
	v_readlane_b32 s92, v253, 8
	v_readlane_b32 s93, v253, 9
	v_readlane_b32 s96, v253, 12
	v_readlane_b32 s97, v253, 13
	v_readlane_b32 s98, v255, 39
	v_readlane_b32 s94, v255, 37
	v_readlane_b32 s88, v255, 27
	s_mov_b64 s[96:97], 0x800
	v_readlane_b32 s99, v255, 40
	v_readlane_b32 s95, v255, 38
	v_readlane_b32 s92, v255, 31
	v_readlane_b32 s89, v255, 28
	v_readlane_b32 s90, v255, 29
	v_readlane_b32 s91, v255, 30
	v_lshl_add_u64 v[0:1], v[0:1], 2, s[84:85]
	v_lshl_add_u64 v[2:3], s[8:9], 2, v[76:77]
	s_mov_b64 s[8:9], 0
	v_mov_b32_e32 v4, v172
	v_readlane_b32 s86, v253, 2
	v_readlane_b32 s87, v253, 3
	v_readlane_b32 s93, v255, 32

; #define LAS __attribute__((address_space(3)))
; DI void p0_prologue(const Args& a, LAS unsigned char* lds, int tid, int wave, int lane, bool first) {
;     ...
;     LAS float* scr = (LAS float*)(lds + wave * 16384);
;     const int gw = blockIdx.x * 8 + wave, NGW = gridDim.x * 8;
;     constexpr int I_UP = (D / 64) * (NUP / 32), I_DN = (FF / 64) * (D / 32), I_IN = (D / 64) * (NIN / 32), I_OUT = (D / 64) * (D / 32);
;     constexpr int NITEMS = 2 * I_UP + 2 * I_DN + I_IN + I_OUT;
;     for (int it = gw; it < NITEMS; it += NGW) {
;         int r = it;
.LBB0_717:
	s_or_b64 exec, exec, s[4:5]
	v_readlane_b32 s8, v255, 49
	s_add_i32 s100, s8, s34
	s_mov_b32 s101, 0
	s_cmpk_lg_i32 s92, 0x100
	s_cbranch_scc1 .Ltr_setup
	s_movk_i32 s101, 0x380
	s_cmpk_lt_i32 s34, 0x480
	s_cbranch_scc0 .Ltr_setup
	s_movk_i32 s101, 0x7000
